# out-proj epilogue gates: block-4 gate reuses block-2 value (same address), block-3 gate load issued one block early into a spare register; removes two vmcnt(0) per tile; on top of v50
# baseline (speedup 1.0000x reference)
; DI int crow(int i, int h) { return (i & 3) + 8 * (i >> 2) + 4 * h; }
; DI void phase_out(CP p, const Ptrs& w, int l, bf16_t* sA, bf16_t* sB) {
;     ...
;     const float* gate = w.mod + (l * 3 + (isctx ? 2 : b)) * 6144 + 4096;
; #pragma unroll
;     for (int mi = 0; mi < 2; ++mi)
; #pragma unroll
;       for (int ni = 0; ni < 2; ++ni) {
;         int col = n0 + wn * 64 + ni * 32 + r;
;         float gt = gate[col];
; #pragma unroll
;         for (int i = 0; i < 16; ++i) {
;           int ii = ib + wm * 64 + mi * 32 + crow(i, h);
;           const float* src = xrow(p, w, l, b * TPB + ii);
;           float* dstp = isctx ? w.xc1 + (size_t)(b * CTXL + ii) * DM : p.out + (size_t)(b * 8192 + ii - CTXL) * DM;
;           dstp[col] = src[col] + gt * acc[mi][ni][i];
;         }
;       }
.LBB0_1147:
	v_ashrrev_i32_e32 v49, 31, v48
	v_lshlrev_b64 v[48:49], 13, v[48:49]
	v_lshl_add_u64 v[48:49], v[88:89], 0, v[48:49]
	v_lshl_add_u64 v[48:49], v[48:49], 0, v[66:67]
	v_add_u32_e32 v48, s39, v62
	v_ashrrev_i32_e32 v49, 31, v48
	v_lshlrev_b64 v[48:49], 13, v[48:49]
	v_or_b32_e32 v126, 32, v64
	v_lshl_add_u64 v[48:49], s[4:5], 0, v[48:49]
	v_ashrrev_i32_e32 v127, 31, v126
	v_lshl_add_u64 v[88:89], v[48:49], 0, v[66:67]
	v_lshl_add_u64 v[48:49], v[126:127], 2, s[6:7]
	s_and_b64 vcc, exec, s[40:41]
	s_mov_b64 s[6:7], -1
	s_waitcnt vmcnt(31)
	v_fma_f32 v91, v63, v90, v209
	global_store_dword v[88:89], v91, off
	s_waitcnt vmcnt(32)
	v_add_u32_e32 v171, 0x40000, v170
	global_load_dword v194, v171, s[100:101]
	v_add_u32_e32 v171, 0x42000, v170
	global_load_dword v195, v171, s[100:101]
	v_add_u32_e32 v171, 0x44000, v170
	global_load_dword v196, v171, s[100:101]
	v_add_u32_e32 v171, 0x46000, v170
	global_load_dword v197, v171, s[100:101]
	v_add_u32_e32 v171, 0x50000, v170
	global_load_dword v198, v171, s[100:101]
	v_add_u32_e32 v171, 0x52000, v170
	global_load_dword v199, v171, s[100:101]
	v_add_u32_e32 v171, 0x54000, v170
	global_load_dword v200, v171, s[100:101]
	v_add_u32_e32 v171, 0x56000, v170
	global_load_dword v201, v171, s[100:101]
	v_add_u32_e32 v171, 0x60000, v170
	global_load_dword v202, v171, s[100:101]
	v_add_u32_e32 v171, 0x62000, v170
	global_load_dword v203, v171, s[100:101]
	v_add_u32_e32 v171, 0x64000, v170
	global_load_dword v204, v171, s[100:101]
	v_add_u32_e32 v171, 0x66000, v170
	global_load_dword v205, v171, s[100:101]
	v_add_u32_e32 v171, 0x70000, v170
	global_load_dword v206, v171, s[100:101]
	v_add_u32_e32 v171, 0x72000, v170
	global_load_dword v207, v171, s[100:101]
	v_add_u32_e32 v171, 0x74000, v170
	global_load_dword v208, v171, s[100:101]
	v_add_u32_e32 v171, 0x76000, v170
	global_load_dword v209, v171, s[100:101]
	global_load_dword v169, v[68:69], off
	global_load_dword v125, v[48:49], off
	s_and_b64 vcc, exec, s[40:41]
	s_mov_b64 s[6:7], -1
	s_waitcnt vmcnt(0)
	v_fma_f32 v62, v32, v125, v210
	global_store_dword v[70:71], v62, off offset:128
	s_and_b64 vcc, exec, s[40:41]
	s_mov_b64 s[6:7], -1
	s_waitcnt vmcnt(1)
	v_fma_f32 v32, v33, v125, v211
	global_store_dword v[72:73], v32, off offset:128
	s_and_b64 vcc, exec, s[40:41]
	s_mov_b64 s[6:7], -1
	s_waitcnt vmcnt(2)
	v_fma_f32 v32, v34, v125, v212
	global_store_dword v[74:75], v32, off offset:128
	s_and_b64 vcc, exec, s[40:41]
	s_mov_b64 s[6:7], -1
	s_waitcnt vmcnt(3)
	v_fma_f32 v32, v35, v125, v213
	global_store_dword v[50:51], v32, off offset:128
	s_and_b64 vcc, exec, s[40:41]
	s_mov_b64 s[6:7], -1
	s_waitcnt vmcnt(4)
	v_fma_f32 v32, v36, v125, v172
	global_store_dword v[76:77], v32, off offset:128
	s_and_b64 vcc, exec, s[40:41]
	s_mov_b64 s[6:7], -1
	s_waitcnt vmcnt(5)
	v_fma_f32 v32, v37, v125, v173
	global_store_dword v[52:53], v32, off offset:128
	s_and_b64 vcc, exec, s[40:41]
	s_mov_b64 s[6:7], -1
	s_waitcnt vmcnt(6)
	v_fma_f32 v32, v38, v125, v174
	global_store_dword v[78:79], v32, off offset:128
	s_and_b64 vcc, exec, s[40:41]
	s_mov_b64 s[6:7], -1
	s_waitcnt vmcnt(7)
	v_fma_f32 v32, v39, v125, v175
	global_store_dword v[54:55], v32, off offset:128
	s_and_b64 vcc, exec, s[40:41]
	s_mov_b64 s[6:7], -1
	s_waitcnt vmcnt(8)
	v_fma_f32 v32, v40, v125, v176
	global_store_dword v[80:81], v32, off offset:128
	s_and_b64 vcc, exec, s[40:41]
	s_mov_b64 s[6:7], -1
	s_waitcnt vmcnt(9)
	v_fma_f32 v32, v41, v125, v177
	global_store_dword v[56:57], v32, off offset:128
	s_and_b64 vcc, exec, s[40:41]
	s_mov_b64 s[6:7], -1
	s_waitcnt vmcnt(10)
	v_fma_f32 v32, v42, v125, v178
	global_store_dword v[82:83], v32, off offset:128
	s_and_b64 vcc, exec, s[40:41]
	s_mov_b64 s[6:7], -1
	s_waitcnt vmcnt(11)
	v_fma_f32 v32, v43, v125, v179
	global_store_dword v[58:59], v32, off offset:128
	s_and_b64 vcc, exec, s[40:41]
	s_mov_b64 s[6:7], -1
	s_waitcnt vmcnt(12)
	v_fma_f32 v32, v44, v125, v132
	global_store_dword v[84:85], v32, off offset:128
	s_and_b64 vcc, exec, s[40:41]
	s_mov_b64 s[6:7], -1
	s_waitcnt vmcnt(13)
	v_fma_f32 v32, v45, v125, v133
	global_store_dword v[60:61], v32, off offset:128
	s_and_b64 vcc, exec, s[40:41]
	s_mov_b64 s[6:7], -1
	s_waitcnt vmcnt(14)
	v_fma_f32 v32, v46, v125, v134
	global_store_dword v[86:87], v32, off offset:128
	s_cbranch_vccnz .LBB0_1333
	s_and_saveexec_b64 s[6:7], s[72:73]
	s_xor_b64 s[6:7], exec, s[6:7]
	v_lshlrev_b32_e32 v32, 13, v123
	s_movk_i32 s10, 0xff00
	v_add3_u32 v32, v32, v124, s10
	s_or_saveexec_b64 s[6:7], s[6:7]
	v_mov_b64_e32 v[34:35], s[76:77]
	s_xor_b64 exec, exec, s[6:7]
	v_lshl_add_u32 v32, v123, 8, v124
	v_mov_b64_e32 v[34:35], s[12:13]
	s_or_b64 exec, exec, s[6:7]
	s_mov_b64 s[6:7], 0

; DI int crow(int i, int h) { return (i & 3) + 8 * (i >> 2) + 4 * h; }
; DI void phase_out(CP p, const Ptrs& w, int l, bf16_t* sA, bf16_t* sB) {
;     ...
;     const float* gate = w.mod + (l * 3 + (isctx ? 2 : b)) * 6144 + 4096;
; #pragma unroll
;     for (int mi = 0; mi < 2; ++mi)
; #pragma unroll
;       for (int ni = 0; ni < 2; ++ni) {
;         int col = n0 + wn * 64 + ni * 32 + r;
;         float gt = gate[col];
; #pragma unroll
;         for (int i = 0; i < 16; ++i) {
;           int ii = ib + wm * 64 + mi * 32 + crow(i, h);
;           const float* src = xrow(p, w, l, b * TPB + ii);
;           float* dstp = isctx ? w.xc1 + (size_t)(b * CTXL + ii) * DM : p.out + (size_t)(b * 8192 + ii - CTXL) * DM;
;           dstp[col] = src[col] + gt * acc[mi][ni][i];
;         }
;       }
.LBB0_1339:
	v_ashrrev_i32_e32 v33, 31, v32
	v_lshlrev_b64 v[32:33], 13, v[32:33]
	v_lshl_add_u64 v[32:33], v[34:35], 0, v[32:33]
	v_lshl_add_u64 v[32:33], v[64:65], 2, v[32:33]
	v_or_b32_e32 v52, 32, v92
	v_or_b32_e32 v36, v52, v164
	s_and_b64 vcc, exec, s[40:41]
	s_mov_b64 s[6:7], -1
	s_waitcnt vmcnt(15)
	v_fma_f32 v32, v47, v125, v135
	global_store_dword v[88:89], v32, off offset:128
	s_waitcnt vmcnt(32)
	v_add_u32_e32 v171, 0x40080, v170
	global_load_dword v210, v171, s[100:101]
	v_add_u32_e32 v171, 0x42080, v170
	global_load_dword v211, v171, s[100:101]
	v_add_u32_e32 v171, 0x44080, v170
	global_load_dword v212, v171, s[100:101]
	v_add_u32_e32 v171, 0x46080, v170
	global_load_dword v213, v171, s[100:101]
	v_add_u32_e32 v171, 0x50080, v170
	global_load_dword v172, v171, s[100:101]
	v_add_u32_e32 v171, 0x52080, v170
	global_load_dword v173, v171, s[100:101]
	v_add_u32_e32 v171, 0x54080, v170
	global_load_dword v174, v171, s[100:101]
	v_add_u32_e32 v171, 0x56080, v170
	global_load_dword v175, v171, s[100:101]
	v_add_u32_e32 v171, 0x60080, v170
	global_load_dword v176, v171, s[100:101]
	v_add_u32_e32 v171, 0x62080, v170
	global_load_dword v177, v171, s[100:101]
	v_add_u32_e32 v171, 0x64080, v170
	global_load_dword v178, v171, s[100:101]
	v_add_u32_e32 v171, 0x66080, v170
	global_load_dword v179, v171, s[100:101]
	v_add_u32_e32 v171, 0x70080, v170
	global_load_dword v132, v171, s[100:101]
	v_add_u32_e32 v171, 0x72080, v170
	global_load_dword v133, v171, s[100:101]
	v_add_u32_e32 v171, 0x74080, v170
	global_load_dword v134, v171, s[100:101]
	s_waitcnt vmcnt(32)
	v_mov_b32_e32 v58, v169
	v_add_u32_e32 v32, s38, v36
	v_mul_hi_i32 v33, v32, s0
	v_lshrrev_b32_e32 v34, 31, v33
	v_ashrrev_i32_e32 v33, 11, v33
	v_add_u32_e32 v54, v33, v34
	v_mad_i32_i24 v55, v54, s1, v32
	v_cmp_lt_i32_e64 s[42:43], s37, v55
	v_add_u32_e32 v34, s39, v36
	v_ashrrev_i32_e32 v35, 31, v34
	v_lshlrev_b64 v[34:35], 13, v[34:35]
	v_lshl_add_u64 v[34:35], s[4:5], 0, v[34:35]
	v_lshl_add_u64 v[32:33], v[34:35], 0, v[66:67]
	s_mov_b64 s[6:7], -1
	s_and_b64 vcc, exec, s[40:41]
	s_waitcnt vmcnt(48)
	v_fma_f32 v36, v16, v58, v194
	v_or_b32_e32 v16, v52, v167
	v_add_u32_e32 v34, s38, v16
	v_mul_hi_i32 v35, v34, s0
	global_store_dword v[32:33], v36, off
	v_lshrrev_b32_e32 v36, 31, v35
	v_ashrrev_i32_e32 v35, 11, v35
	v_add_u32_e32 v56, v35, v36
	v_mad_i32_i24 v57, v56, s1, v34
	v_cmp_lt_i32_e64 s[44:45], s37, v57
	v_add_u32_e32 v36, s39, v16
	v_ashrrev_i32_e32 v37, 31, v36
	v_lshlrev_b64 v[36:37], 13, v[36:37]
	v_lshl_add_u64 v[36:37], s[4:5], 0, v[36:37]
	v_or_b32_e32 v38, v52, v180
	s_mov_b64 s[6:7], -1
	s_and_b64 vcc, exec, s[40:41]
	s_waitcnt vmcnt(48)
	v_fma_f32 v34, v17, v58, v195
	v_lshl_add_u64 v[16:17], v[36:37], 0, v[66:67]
	global_store_dword v[16:17], v34, off
	v_add_u32_e32 v34, s38, v38
	v_mul_hi_i32 v35, v34, s0
	v_lshrrev_b32_e32 v36, 31, v35
	v_ashrrev_i32_e32 v35, 11, v35
	v_add_u32_e32 v59, v35, v36
	v_mad_i32_i24 v60, v59, s1, v34
	v_cmp_lt_i32_e64 s[46:47], s37, v60
	v_add_u32_e32 v36, s39, v38
	v_ashrrev_i32_e32 v37, 31, v36
	v_lshlrev_b64 v[36:37], 13, v[36:37]
	v_lshl_add_u64 v[36:37], s[4:5], 0, v[36:37]
	v_lshl_add_u64 v[34:35], v[36:37], 0, v[66:67]
	s_mov_b64 s[6:7], -1
	s_and_b64 vcc, exec, s[40:41]
	s_waitcnt vmcnt(48)
	v_fma_f32 v38, v18, v58, v196
	v_or_b32_e32 v18, v52, v181
	v_add_u32_e32 v36, s38, v18
	v_mul_hi_i32 v37, v36, s0
	global_store_dword v[34:35], v38, off
	v_lshrrev_b32_e32 v38, 31, v37
	v_ashrrev_i32_e32 v37, 11, v37
	v_add_u32_e32 v61, v37, v38
	v_mad_i32_i24 v62, v61, s1, v36
	v_cmp_lt_i32_e64 s[48:49], s37, v62
	v_add_u32_e32 v38, s39, v18
	v_ashrrev_i32_e32 v39, 31, v38
	v_lshlrev_b64 v[38:39], 13, v[38:39]
	v_lshl_add_u64 v[38:39], s[4:5], 0, v[38:39]
	v_or_b32_e32 v40, v52, v182
	s_mov_b64 s[6:7], -1
	s_and_b64 vcc, exec, s[40:41]
	s_waitcnt vmcnt(48)
	v_fma_f32 v36, v19, v58, v197
	v_lshl_add_u64 v[18:19], v[38:39], 0, v[66:67]
	global_store_dword v[18:19], v36, off
	v_add_u32_e32 v36, s38, v40
	v_mul_hi_i32 v37, v36, s0
	v_lshrrev_b32_e32 v38, 31, v37
	v_ashrrev_i32_e32 v37, 11, v37
	v_add_u32_e32 v63, v37, v38
	v_mad_i32_i24 v68, v63, s1, v36
	v_cmp_lt_i32_e64 s[50:51], s37, v68
	v_add_u32_e32 v38, s39, v40
	v_ashrrev_i32_e32 v39, 31, v38
	v_lshlrev_b64 v[38:39], 13, v[38:39]
	v_lshl_add_u64 v[38:39], s[4:5], 0, v[38:39]
	v_lshl_add_u64 v[36:37], v[38:39], 0, v[66:67]
	s_mov_b64 s[6:7], -1
	s_and_b64 vcc, exec, s[40:41]
	s_waitcnt vmcnt(48)
	v_fma_f32 v40, v20, v58, v198
	v_or_b32_e32 v20, v52, v183
	v_add_u32_e32 v38, s38, v20
	v_mul_hi_i32 v39, v38, s0
	global_store_dword v[36:37], v40, off
	v_lshrrev_b32_e32 v40, 31, v39
	v_ashrrev_i32_e32 v39, 11, v39
	v_add_u32_e32 v69, v39, v40
	v_mad_i32_i24 v70, v69, s1, v38
	v_cmp_lt_i32_e64 s[52:53], s37, v70
	v_add_u32_e32 v40, s39, v20
	v_ashrrev_i32_e32 v41, 31, v40
	v_lshlrev_b64 v[40:41], 13, v[40:41]
	v_lshl_add_u64 v[40:41], s[4:5], 0, v[40:41]
	v_or_b32_e32 v42, v52, v184
	s_mov_b64 s[6:7], -1
	s_and_b64 vcc, exec, s[40:41]
	s_waitcnt vmcnt(48)
	v_fma_f32 v38, v21, v58, v199
	v_lshl_add_u64 v[20:21], v[40:41], 0, v[66:67]
	global_store_dword v[20:21], v38, off
	v_add_u32_e32 v38, s38, v42
	v_mul_hi_i32 v39, v38, s0
	v_lshrrev_b32_e32 v40, 31, v39
	v_ashrrev_i32_e32 v39, 11, v39
	v_add_u32_e32 v71, v39, v40
	v_mad_i32_i24 v72, v71, s1, v38
	v_cmp_lt_i32_e64 s[54:55], s37, v72
	v_add_u32_e32 v40, s39, v42
	v_ashrrev_i32_e32 v41, 31, v40
	v_lshlrev_b64 v[40:41], 13, v[40:41]
	v_lshl_add_u64 v[40:41], s[4:5], 0, v[40:41]
	v_lshl_add_u64 v[38:39], v[40:41], 0, v[66:67]
	s_mov_b64 s[6:7], -1
	s_and_b64 vcc, exec, s[40:41]
	s_waitcnt vmcnt(48)
; DI int crow(int i, int h) { return (i & 3) + 8 * (i >> 2) + 4 * h; }
; DI void phase_out(CP p, const Ptrs& w, int l, bf16_t* sA, bf16_t* sB) {
;     ...
;     const float* gate = w.mod + (l * 3 + (isctx ? 2 : b)) * 6144 + 4096;
; #pragma unroll
;     for (int mi = 0; mi < 2; ++mi)
; #pragma unroll
;       for (int ni = 0; ni < 2; ++ni) {
;         int col = n0 + wn * 64 + ni * 32 + r;
;         float gt = gate[col];
; #pragma unroll
;         for (int i = 0; i < 16; ++i) {
;           int ii = ib + wm * 64 + mi * 32 + crow(i, h);
;           const float* src = xrow(p, w, l, b * TPB + ii);
;           float* dstp = isctx ? w.xc1 + (size_t)(b * CTXL + ii) * DM : p.out + (size_t)(b * 8192 + ii - CTXL) * DM;
;           dstp[col] = src[col] + gt * acc[mi][ni][i];
;         }
;       }
	v_fma_f32 v42, v22, v58, v200
	v_or_b32_e32 v22, v52, v185
	v_add_u32_e32 v40, s38, v22
	v_mul_hi_i32 v41, v40, s0
	global_store_dword v[38:39], v42, off
	v_lshrrev_b32_e32 v42, 31, v41
	v_ashrrev_i32_e32 v41, 11, v41
	v_add_u32_e32 v73, v41, v42
	v_mad_i32_i24 v74, v73, s1, v40
	v_cmp_lt_i32_e64 s[56:57], s37, v74
	v_add_u32_e32 v42, s39, v22
	v_ashrrev_i32_e32 v43, 31, v42
	v_lshlrev_b64 v[42:43], 13, v[42:43]
	v_lshl_add_u64 v[42:43], s[4:5], 0, v[42:43]
	v_or_b32_e32 v44, v52, v186
	s_mov_b64 s[6:7], -1
	s_and_b64 vcc, exec, s[40:41]
	s_waitcnt vmcnt(48)
	v_fma_f32 v40, v23, v58, v201
	v_lshl_add_u64 v[22:23], v[42:43], 0, v[66:67]
	global_store_dword v[22:23], v40, off
	v_add_u32_e32 v40, s38, v44
	v_mul_hi_i32 v41, v40, s0
	v_lshrrev_b32_e32 v42, 31, v41
	v_ashrrev_i32_e32 v41, 11, v41
	v_add_u32_e32 v75, v41, v42
	v_mad_i32_i24 v76, v75, s1, v40
	v_cmp_lt_i32_e64 s[58:59], s37, v76
	v_add_u32_e32 v42, s39, v44
	v_ashrrev_i32_e32 v43, 31, v42
	v_lshlrev_b64 v[42:43], 13, v[42:43]
	v_lshl_add_u64 v[42:43], s[4:5], 0, v[42:43]
	v_lshl_add_u64 v[40:41], v[42:43], 0, v[66:67]
	s_mov_b64 s[6:7], -1
	s_and_b64 vcc, exec, s[40:41]
	s_waitcnt vmcnt(48)
	v_fma_f32 v44, v24, v58, v202
	v_or_b32_e32 v24, v52, v187
	v_add_u32_e32 v42, s38, v24
	v_mul_hi_i32 v43, v42, s0
	global_store_dword v[40:41], v44, off
	v_lshrrev_b32_e32 v44, 31, v43
	v_ashrrev_i32_e32 v43, 11, v43
	v_add_u32_e32 v77, v43, v44
	v_mad_i32_i24 v78, v77, s1, v42
	v_cmp_lt_i32_e64 s[60:61], s37, v78
	v_add_u32_e32 v44, s39, v24
	v_ashrrev_i32_e32 v45, 31, v44
	v_lshlrev_b64 v[44:45], 13, v[44:45]
	v_lshl_add_u64 v[44:45], s[4:5], 0, v[44:45]
	v_or_b32_e32 v46, v52, v188
	s_mov_b64 s[6:7], -1
	s_and_b64 vcc, exec, s[40:41]
	s_waitcnt vmcnt(48)
	v_fma_f32 v42, v25, v58, v203
	v_lshl_add_u64 v[24:25], v[44:45], 0, v[66:67]
	global_store_dword v[24:25], v42, off
	v_add_u32_e32 v42, s38, v46
	v_mul_hi_i32 v43, v42, s0
	v_lshrrev_b32_e32 v44, 31, v43
	v_ashrrev_i32_e32 v43, 11, v43
	v_add_u32_e32 v79, v43, v44
	v_mad_i32_i24 v80, v79, s1, v42
	v_cmp_lt_i32_e64 s[62:63], s37, v80
	v_add_u32_e32 v44, s39, v46
	v_ashrrev_i32_e32 v45, 31, v44
	v_lshlrev_b64 v[44:45], 13, v[44:45]
	v_lshl_add_u64 v[44:45], s[4:5], 0, v[44:45]
	v_lshl_add_u64 v[42:43], v[44:45], 0, v[66:67]
	s_mov_b64 s[6:7], -1
	s_and_b64 vcc, exec, s[40:41]
	s_waitcnt vmcnt(48)
	v_fma_f32 v46, v26, v58, v204
	v_or_b32_e32 v26, v52, v189
	v_add_u32_e32 v44, s38, v26
	v_mul_hi_i32 v45, v44, s0
	global_store_dword v[42:43], v46, off
	v_lshrrev_b32_e32 v46, 31, v45
	v_ashrrev_i32_e32 v45, 11, v45
	v_add_u32_e32 v81, v45, v46
	v_mad_i32_i24 v82, v81, s1, v44
	v_cmp_lt_i32_e64 s[64:65], s37, v82
	v_add_u32_e32 v46, s39, v26
	v_ashrrev_i32_e32 v47, 31, v46
	v_lshlrev_b64 v[46:47], 13, v[46:47]
	v_lshl_add_u64 v[46:47], s[4:5], 0, v[46:47]
	v_or_b32_e32 v50, v52, v190
	s_mov_b64 s[6:7], -1
	s_and_b64 vcc, exec, s[40:41]
	s_waitcnt vmcnt(48)
	v_fma_f32 v44, v27, v58, v205
	v_lshl_add_u64 v[26:27], v[46:47], 0, v[66:67]
	global_store_dword v[26:27], v44, off
	v_add_u32_e32 v44, s38, v50
	v_mul_hi_i32 v45, v44, s0
	v_lshrrev_b32_e32 v46, 31, v45
	v_ashrrev_i32_e32 v45, 11, v45
	v_add_u32_e32 v83, v45, v46
	v_mad_i32_i24 v84, v83, s1, v44
	v_cmp_lt_i32_e64 s[66:67], s37, v84
	v_add_u32_e32 v46, s39, v50
	v_ashrrev_i32_e32 v47, 31, v46
	v_lshlrev_b64 v[46:47], 13, v[46:47]
	v_lshl_add_u64 v[46:47], s[4:5], 0, v[46:47]
	v_lshl_add_u64 v[44:45], v[46:47], 0, v[66:67]
	s_mov_b64 s[6:7], -1
	s_and_b64 vcc, exec, s[40:41]
	s_waitcnt vmcnt(48)
	v_fma_f32 v50, v28, v58, v206
	v_or_b32_e32 v28, v52, v191
	v_add_u32_e32 v46, s38, v28
	v_mul_hi_i32 v47, v46, s0
	global_store_dword v[44:45], v50, off
	v_lshrrev_b32_e32 v50, 31, v47
	v_ashrrev_i32_e32 v47, 11, v47
	v_add_u32_e32 v85, v47, v50
	v_mad_i32_i24 v86, v85, s1, v46
	v_cmp_lt_i32_e64 s[68:69], s37, v86
	v_add_u32_e32 v50, s39, v28
	v_ashrrev_i32_e32 v51, 31, v50
	v_lshlrev_b64 v[50:51], 13, v[50:51]
	v_lshl_add_u64 v[50:51], s[4:5], 0, v[50:51]
	v_or_b32_e32 v53, v52, v192
	s_mov_b64 s[6:7], -1
	s_and_b64 vcc, exec, s[40:41]
	s_waitcnt vmcnt(48)
; DI int crow(int i, int h) { return (i & 3) + 8 * (i >> 2) + 4 * h; }
; DI void phase_out(CP p, const Ptrs& w, int l, bf16_t* sA, bf16_t* sB) {
;     ...
;     const float* gate = w.mod + (l * 3 + (isctx ? 2 : b)) * 6144 + 4096;
; #pragma unroll
;     for (int mi = 0; mi < 2; ++mi)
; #pragma unroll
;       for (int ni = 0; ni < 2; ++ni) {
;         int col = n0 + wn * 64 + ni * 32 + r;
;         float gt = gate[col];
; #pragma unroll
;         for (int i = 0; i < 16; ++i) {
;           int ii = ib + wm * 64 + mi * 32 + crow(i, h);
;           const float* src = xrow(p, w, l, b * TPB + ii);
;           float* dstp = isctx ? w.xc1 + (size_t)(b * CTXL + ii) * DM : p.out + (size_t)(b * 8192 + ii - CTXL) * DM;
;           dstp[col] = src[col] + gt * acc[mi][ni][i];
;         }
;       }
	v_fma_f32 v46, v29, v58, v207
	v_lshl_add_u64 v[28:29], v[50:51], 0, v[66:67]
	global_store_dword v[28:29], v46, off
	v_add_u32_e32 v46, s38, v53
	v_mul_hi_i32 v47, v46, s0
	v_lshrrev_b32_e32 v50, 31, v47
	v_ashrrev_i32_e32 v47, 11, v47
	v_add_u32_e32 v87, v47, v50
	v_mad_i32_i24 v88, v87, s1, v46
	v_cmp_lt_i32_e64 s[70:71], s37, v88
	v_add_u32_e32 v50, s39, v53
	v_ashrrev_i32_e32 v51, 31, v50
	v_lshlrev_b64 v[50:51], 13, v[50:51]
	v_lshl_add_u64 v[50:51], s[4:5], 0, v[50:51]
	v_lshl_add_u64 v[46:47], v[50:51], 0, v[66:67]
	s_mov_b64 s[6:7], -1
	s_and_b64 vcc, exec, s[40:41]
	s_waitcnt vmcnt(48)
	v_fma_f32 v53, v30, v58, v208
	v_or_b32_e32 v30, v52, v193
	v_add_u32_e32 v50, s38, v30
	v_mul_hi_i32 v51, v50, s0
	v_lshrrev_b32_e32 v52, 31, v51
	v_ashrrev_i32_e32 v51, 11, v51
	v_add_u32_e32 v89, v51, v52
	v_mad_i32_i24 v90, v89, s1, v50
	v_cmp_lt_i32_e64 s[72:73], s37, v90
	global_store_dword v[46:47], v53, off
	v_add_u32_e32 v50, s39, v30
	v_ashrrev_i32_e32 v51, 31, v50
	v_lshlrev_b64 v[50:51], 13, v[50:51]
	v_lshl_add_u64 v[50:51], s[4:5], 0, v[50:51]
	s_and_b64 vcc, exec, s[40:41]
	s_mov_b64 s[4:5], -1
	s_waitcnt vmcnt(48)
	v_fma_f32 v52, v31, v58, v209
	v_lshl_add_u64 v[30:31], v[50:51], 0, v[66:67]
	global_store_dword v[30:31], v52, off
	v_mov_b32_e32 v52, v125
	s_and_b64 vcc, exec, s[40:41]
	s_mov_b64 s[4:5], -1
	v_readlane_b32 s42, v255, 3
	s_waitcnt vmcnt(30)
	v_fma_f32 v48, v0, v52, v210
	global_store_dword v[32:33], v48, off offset:128
	s_and_b64 vcc, exec, s[40:41]
	s_mov_b64 s[4:5], -1
	s_waitcnt vmcnt(30)
	v_fma_f32 v0, v1, v52, v211
	global_store_dword v[16:17], v0, off offset:128
	s_and_b64 vcc, exec, s[40:41]
	s_mov_b64 s[4:5], -1
	s_waitcnt vmcnt(30)
	v_fma_f32 v0, v2, v52, v212
	global_store_dword v[34:35], v0, off offset:128
	s_and_b64 vcc, exec, s[40:41]
	s_mov_b64 s[4:5], -1
	s_waitcnt vmcnt(30)
	v_fma_f32 v0, v3, v52, v213
	global_store_dword v[18:19], v0, off offset:128
	s_and_b64 vcc, exec, s[40:41]
	s_mov_b64 s[4:5], -1
	s_waitcnt vmcnt(30)
	v_fma_f32 v0, v4, v52, v172
	global_store_dword v[36:37], v0, off offset:128
	s_and_b64 vcc, exec, s[40:41]
	s_mov_b64 s[4:5], -1
	s_waitcnt vmcnt(30)
	v_fma_f32 v0, v5, v52, v173
	global_store_dword v[20:21], v0, off offset:128
	s_and_b64 vcc, exec, s[40:41]
	s_mov_b64 s[4:5], -1
	s_waitcnt vmcnt(30)
	v_fma_f32 v0, v6, v52, v174
	global_store_dword v[38:39], v0, off offset:128
	s_and_b64 vcc, exec, s[40:41]
	s_mov_b64 s[4:5], -1
	s_waitcnt vmcnt(30)
	v_fma_f32 v0, v7, v52, v175
	global_store_dword v[22:23], v0, off offset:128
	s_and_b64 vcc, exec, s[40:41]
	s_mov_b64 s[4:5], -1
	s_waitcnt vmcnt(30)
	v_fma_f32 v0, v8, v52, v176
	global_store_dword v[40:41], v0, off offset:128
	s_and_b64 vcc, exec, s[40:41]
	s_mov_b64 s[4:5], -1
	v_readlane_b32 s61, v254, 51
	s_waitcnt vmcnt(30)
	v_fma_f32 v0, v9, v52, v177
	global_store_dword v[24:25], v0, off offset:128
	s_and_b64 vcc, exec, s[40:41]
	s_mov_b64 s[4:5], -1
	s_waitcnt vmcnt(30)
	v_fma_f32 v0, v10, v52, v178
	global_store_dword v[42:43], v0, off offset:128
	s_and_b64 vcc, exec, s[40:41]
	s_mov_b64 s[4:5], -1
	s_waitcnt vmcnt(30)
	v_fma_f32 v0, v11, v52, v179
	global_store_dword v[26:27], v0, off offset:128
	s_and_b64 vcc, exec, s[40:41]
	s_mov_b64 s[4:5], -1
	s_waitcnt vmcnt(30)
	v_fma_f32 v0, v12, v52, v132
	global_store_dword v[44:45], v0, off offset:128
	s_and_b64 vcc, exec, s[40:41]
	s_mov_b64 s[4:5], -1
	s_waitcnt vmcnt(30)
	v_fma_f32 v0, v13, v52, v133
	global_store_dword v[28:29], v0, off offset:128
	s_and_b64 vcc, exec, s[40:41]
	s_mov_b64 s[4:5], -1
	v_readlane_b32 s41, v255, 1
	s_waitcnt vmcnt(30)
	v_fma_f32 v0, v14, v52, v134
	global_store_dword v[46:47], v0, off offset:128
	s_cbranch_vccnz .LBB0_1717
	s_and_saveexec_b64 s[4:5], s[72:73]
	s_xor_b64 s[4:5], exec, s[4:5]
	v_lshlrev_b32_e32 v0, 13, v89
	s_movk_i32 s6, 0xff00
	v_add3_u32 v0, v0, v90, s6
	s_or_saveexec_b64 s[4:5], s[4:5]
	v_mov_b64_e32 v[2:3], s[76:77]
	s_xor_b64 exec, exec, s[4:5]
	v_lshl_add_u32 v0, v89, 8, v90
	v_mov_b64_e32 v[2:3], s[12:13]
	s_or_b64 exec, exec, s[4:5]
	s_mov_b64 s[4:5], 0
